# pool/conv: depthwise conv rewritten with v_pk_fma_f32 (two outputs per FMA, tap weights resident in registers in two descending layouts), LDS reads batched; pool prefix reads batched
# speedup vs baseline: 1.0169x; 1.0098x over previous
.LBB0_561:
	s_or_b64 exec, exec, s[12:13]
	s_add_u32 s12, s14, 0xbc00000
	s_addc_u32 s13, s15, 0
	s_and_b64 s[14:15], s[60:61], exec
	s_cselect_b32 s0, 0x7c00, 0
	s_add_u32 s30, s27, s0
	s_addc_u32 s31, s26, 0
	s_and_b64 s[14:15], s[60:61], exec
	s_cselect_b32 s0, 0x400, 0
	s_add_u32 s14, s21, s0
	s_addc_u32 s15, s3, 0
	s_add_u32 s20, s20, s0
	v_mov_b32_e32 v1, 2
	s_addc_u32 s21, s1, 0
	v_lshlrev_b32_sdwa v2, v1, v48 dst_sel:DWORD dst_unused:UNUSED_PAD src0_sel:DWORD src1_sel:BYTE_0
	v_lshlrev_b32_e32 v1, 4, v39
	global_load_dword v134, v2, s[14:15]
	global_load_dwordx4 v[20:23], v1, s[20:21]
	v_mov_b32_e32 v3, v0
	v_lshl_add_u64 v[46:47], s[30:31], 0, v[2:3]
	s_mov_b64 s[20:21], 0x1000
	v_ashrrev_i32_e32 v37, 8, v48
	v_lshlrev_b32_sdwa v44, v235, v48 dst_sel:DWORD dst_unused:UNUSED_PAD src0_sel:DWORD src1_sel:BYTE_0
	v_bfe_u32 v138, v48, 6, 2
	v_cmp_gt_u32_sdwa s[14:15], v48, v236 src0_sel:BYTE_0 src1_sel:DWORD
	v_lshl_add_u64 v[48:49], v[46:47], 0, s[20:21]
	s_mov_b64 s[20:21], 0x1400
	v_lshl_add_u64 v[50:51], v[46:47], 0, s[20:21]
	s_mov_b64 s[20:21], 0x1800
	v_lshl_add_u64 v[52:53], v[46:47], 0, s[20:21]
	s_mov_b64 s[20:21], 0x1c00
	v_lshl_add_u64 v[54:55], v[46:47], 0, s[20:21]
	s_mov_b64 s[20:21], 0x2000
	v_lshl_add_u64 v[56:57], v[46:47], 0, s[20:21]
	s_mov_b64 s[20:21], 0x2400
	v_lshl_add_u64 v[58:59], v[46:47], 0, s[20:21]
	s_mov_b64 s[20:21], 0x2800
	v_lshl_add_u64 v[60:61], v[46:47], 0, s[20:21]
	s_mov_b64 s[20:21], 0x2c00
	v_lshl_add_u64 v[62:63], v[46:47], 0, s[20:21]
	s_mov_b64 s[20:21], 0x3000
	v_lshl_add_u64 v[64:65], v[46:47], 0, s[20:21]
	s_mov_b64 s[20:21], 0x3400
	v_lshl_add_u64 v[66:67], v[46:47], 0, s[20:21]
	s_mov_b64 s[20:21], 0x3800
	v_lshl_add_u64 v[68:69], v[46:47], 0, s[20:21]
	s_mov_b64 s[20:21], 0x3c00
	v_lshl_add_u64 v[70:71], v[46:47], 0, s[20:21]
	s_mov_b64 s[20:21], 0x4000
	v_lshl_add_u64 v[72:73], v[46:47], 0, s[20:21]
	s_mov_b64 s[20:21], 0x4400
	v_lshl_add_u64 v[74:75], v[46:47], 0, s[20:21]
	s_mov_b64 s[20:21], 0x4800
	v_lshl_add_u64 v[76:77], v[46:47], 0, s[20:21]
	s_mov_b64 s[20:21], 0x4c00
	v_lshl_add_u64 v[78:79], v[46:47], 0, s[20:21]
	s_mov_b64 s[20:21], 0x5000
	v_lshl_add_u64 v[80:81], v[46:47], 0, s[20:21]
	s_mov_b64 s[20:21], 0x5400
	v_lshl_add_u64 v[82:83], v[46:47], 0, s[20:21]
	s_mov_b64 s[20:21], 0x5800
	v_lshl_add_u64 v[84:85], v[46:47], 0, s[20:21]
	s_mov_b64 s[20:21], 0x5c00
	v_lshlrev_b32_e32 v3, 14, v37
	s_add_i32 s0, 0, 0x10000
	v_lshl_add_u64 v[86:87], v[46:47], 0, s[20:21]
	s_mov_b64 s[20:21], 0x6000
	v_add_u32_e32 v107, s0, v3
	v_readlane_b32 s0, v255, 9
	v_lshl_add_u64 v[88:89], v[46:47], 0, s[20:21]
	s_mov_b64 s[20:21], 0x6400
	v_add_u32_e32 v108, s0, v3
	v_readlane_b32 s0, v255, 10
	v_lshl_add_u64 v[90:91], v[46:47], 0, s[20:21]
	s_mov_b64 s[20:21], 0x6800
	v_add_u32_e32 v109, s0, v3
	v_readlane_b32 s0, v255, 11
	v_lshl_add_u64 v[92:93], v[46:47], 0, s[20:21]
	s_mov_b64 s[20:21], 0x6c00
	v_add_u32_e32 v110, s0, v3
	v_readlane_b32 s0, v255, 12
	v_lshl_add_u64 v[94:95], v[46:47], 0, s[20:21]
	s_mov_b64 s[20:21], 0x7000
	v_add_u32_e32 v111, s0, v3
	v_readlane_b32 s0, v255, 13
	v_lshlrev_b32_e32 v136, 9, v130
	v_lshlrev_b32_e32 v38, 13, v37
	s_lshl_b32 s41, s35, 2
	v_lshl_add_u64 v[96:97], v[46:47], 0, s[20:21]
	s_mov_b64 s[20:21], 0x7400
	v_add_u32_e32 v112, s0, v3
	v_readlane_b32 s0, v255, 14
	v_add_u32_e32 v135, 0, v36
	v_add_u32_e32 v104, 0, v136
	v_add3_u32 v137, 0, v38, v44
	v_lshlrev_b32_e32 v139, 4, v37
	v_mov_b32_e32 v45, v0
	v_add_u32_e32 v140, 0, v1
	v_lshlrev_b32_e32 v1, 9, v131
	v_lshlrev_b32_e32 v105, 9, v132
	v_lshlrev_b32_e32 v106, 9, v133
	v_lshl_add_u64 v[98:99], v[46:47], 0, s[20:21]
	s_mov_b64 s[20:21], 0x7800
	v_add_u32_e32 v37, 0, v3
	v_add_u32_e32 v3, s0, v3
	s_or_b32 s44, s41, 1
	s_or_b32 s46, s41, 2
	s_or_b32 s57, s41, 3
	v_lshlrev_b32_e32 v38, 3, v39
	v_mov_b32_e32 v39, v0
	s_mov_b32 s40, 0
	v_lshl_add_u64 v[44:45], s[12:13], 0, v[44:45]
	v_lshl_add_u64 v[100:101], v[46:47], 0, s[20:21]
	s_lshl_b32 s35, s35, 12
	s_lshl_b32 s45, s44, 10
	s_lshl_b32 s56, s46, 10
	s_lshl_b32 s58, s57, 10
	v_lshl_add_u64 v[102:103], s[12:13], 0, v[38:39]
	v_add_u32_e32 v141, v135, v1
	v_add_u32_e32 v142, v135, v105
	v_add_u32_e32 v143, v135, v106
	v_add_u32_e32 v144, v104, v36
	v_add_u32_e32 v145, v37, v2
	v_add_u32_e32 v146, v107, v2
	v_add_u32_e32 v147, v108, v2
	v_add_u32_e32 v148, v109, v2
	v_add_u32_e32 v149, v110, v2
	v_add_u32_e32 v150, v111, v2
	v_add_u32_e32 v151, v112, v2
	v_add_u32_e32 v152, v3, v2
	global_load_dword v180, v[100:101], off
	global_load_dword v181, v[98:99], off
	global_load_dword v182, v[96:97], off
	global_load_dword v183, v[94:95], off
	global_load_dword v184, v[92:93], off
	global_load_dword v185, v[90:91], off
	global_load_dword v186, v[88:89], off
	global_load_dword v187, v[86:87], off
	global_load_dword v188, v[84:85], off
	global_load_dword v189, v[82:83], off
	global_load_dword v190, v[80:81], off
	global_load_dword v191, v[78:79], off
	global_load_dword v192, v[76:77], off
	global_load_dword v193, v[74:75], off
	global_load_dword v194, v[72:73], off
	global_load_dword v195, v[70:71], off
	global_load_dword v196, v[68:69], off
	global_load_dword v197, v[66:67], off
	global_load_dword v198, v[64:65], off
	global_load_dword v199, v[62:63], off
	global_load_dword v200, v[60:61], off
	global_load_dword v201, v[58:59], off
	global_load_dword v202, v[56:57], off
	global_load_dword v203, v[54:55], off
	global_load_dword v204, v[52:53], off
	global_load_dword v205, v[50:51], off
	global_load_dword v206, v[48:49], off
	global_load_dword v207, v[46:47], off offset:3072
	global_load_dword v208, v[46:47], off offset:2048
	global_load_dword v209, v[46:47], off offset:1024
	global_load_dword v210, v[46:47], off
	v_mov_b32_e32 v211, 0
	s_waitcnt vmcnt(0)
	v_mov_b32_e32 v46, 0
	v_mov_b32_e32 v47, v180
	v_mov_b32_e32 v48, v181
	v_mov_b32_e32 v49, v182
	v_mov_b32_e32 v50, v183
	v_mov_b32_e32 v51, v184
	v_mov_b32_e32 v52, v185
	v_mov_b32_e32 v53, v186
	v_mov_b32_e32 v54, v187
	v_mov_b32_e32 v55, v188
	v_mov_b32_e32 v56, v189
	v_mov_b32_e32 v57, v190
	v_mov_b32_e32 v58, v191
	v_mov_b32_e32 v59, v192
	v_mov_b32_e32 v60, v193
	v_mov_b32_e32 v61, v194
	v_mov_b32_e32 v62, v195
	v_mov_b32_e32 v63, v196
	v_mov_b32_e32 v64, v197
	v_mov_b32_e32 v65, v198
	v_mov_b32_e32 v66, v199
	v_mov_b32_e32 v67, v200
	v_mov_b32_e32 v68, v201
	v_mov_b32_e32 v69, v202
	v_mov_b32_e32 v70, v203
	v_mov_b32_e32 v71, v204
	v_mov_b32_e32 v72, v205
	v_mov_b32_e32 v73, v206
	v_mov_b32_e32 v74, v207
	v_mov_b32_e32 v75, v208
	v_mov_b32_e32 v76, v209
	v_mov_b32_e32 v77, v210
	s_branch .LBB0_563

.LBB0_591:
	ds_read_u16 v78, v137
	ds_read_u16 v79, v137 offset:512
	ds_read_u16 v80, v137 offset:1024
	ds_read_u16 v81, v137 offset:1536
	ds_read_u16 v82, v137 offset:2048
	ds_read_u16 v83, v137 offset:2560
	ds_read_u16 v84, v137 offset:3072
	ds_read_u16 v85, v137 offset:3584
	ds_read_u16 v86, v137 offset:4096
	ds_read_u16 v87, v137 offset:4608
	ds_read_u16 v88, v137 offset:5120
	ds_read_u16 v89, v137 offset:5632
	ds_read_u16 v90, v137 offset:6144
	ds_read_u16 v91, v137 offset:6656
	ds_read_u16 v92, v137 offset:7168
	s_and_b32 s0, s59, 0xffffff00
	s_and_b32 s3, s59, 0x7ffff000
	s_add_i32 s12, s0, 0x100
	s_add_i32 s13, s3, 0x1000
	s_cmpk_lt_i32 s1, 0x100
	s_cselect_b32 s30, s0, s3
	s_cselect_b32 s31, s12, s13
	s_waitcnt lgkmcnt(7)
	v_lshlrev_b32_e32 v78, 16, v78
	v_lshlrev_b32_e32 v79, 16, v79
	v_lshlrev_b32_e32 v80, 16, v80
	v_lshlrev_b32_e32 v81, 16, v81
	v_lshlrev_b32_e32 v82, 16, v82
	v_lshlrev_b32_e32 v83, 16, v83
	v_lshlrev_b32_e32 v84, 16, v84
	v_lshlrev_b32_e32 v85, 16, v85
	ds_read_u16 v93, v137 offset:7680
	ds_read_u16 v94, v137 offset:8192
	ds_read_u16 v95, v137 offset:8704
	ds_read_u16 v96, v137 offset:9216
	ds_read_u16 v97, v137 offset:9728
	ds_read_u16 v98, v137 offset:10240
	ds_read_u16 v99, v137 offset:10752
	ds_read_u16 v100, v137 offset:11264
	v_pk_fma_f32 v[104:105], v[78:79], v[210:211], v[134:135] op_sel:[0,0,0] op_sel_hi:[0,1,0]
	v_pk_fma_f32 v[104:105], v[78:79], v[76:77], v[104:105] op_sel:[1,0,0] op_sel_hi:[1,1,1]
	v_pk_fma_f32 v[104:105], v[80:81], v[208:209], v[104:105] op_sel:[0,0,0] op_sel_hi:[0,1,1]
	v_pk_fma_f32 v[106:107], v[80:81], v[210:211], v[134:135] op_sel:[0,0,0] op_sel_hi:[0,1,0]
	v_pk_fma_f32 v[104:105], v[80:81], v[74:75], v[104:105] op_sel:[1,0,0] op_sel_hi:[1,1,1]
	v_pk_fma_f32 v[106:107], v[80:81], v[76:77], v[106:107] op_sel:[1,0,0] op_sel_hi:[1,1,1]
	v_pk_fma_f32 v[104:105], v[82:83], v[206:207], v[104:105] op_sel:[0,0,0] op_sel_hi:[0,1,1]
	v_pk_fma_f32 v[106:107], v[82:83], v[208:209], v[106:107] op_sel:[0,0,0] op_sel_hi:[0,1,1]
	v_pk_fma_f32 v[108:109], v[82:83], v[210:211], v[134:135] op_sel:[0,0,0] op_sel_hi:[0,1,0]
	v_pk_fma_f32 v[104:105], v[82:83], v[72:73], v[104:105] op_sel:[1,0,0] op_sel_hi:[1,1,1]
	v_pk_fma_f32 v[106:107], v[82:83], v[74:75], v[106:107] op_sel:[1,0,0] op_sel_hi:[1,1,1]
	v_pk_fma_f32 v[108:109], v[82:83], v[76:77], v[108:109] op_sel:[1,0,0] op_sel_hi:[1,1,1]
	v_pk_fma_f32 v[104:105], v[84:85], v[204:205], v[104:105] op_sel:[0,0,0] op_sel_hi:[0,1,1]
	v_pk_fma_f32 v[106:107], v[84:85], v[206:207], v[106:107] op_sel:[0,0,0] op_sel_hi:[0,1,1]
	v_pk_fma_f32 v[108:109], v[84:85], v[208:209], v[108:109] op_sel:[0,0,0] op_sel_hi:[0,1,1]
	v_pk_fma_f32 v[110:111], v[84:85], v[210:211], v[134:135] op_sel:[0,0,0] op_sel_hi:[0,1,0]
	v_pk_fma_f32 v[104:105], v[84:85], v[70:71], v[104:105] op_sel:[1,0,0] op_sel_hi:[1,1,1]
	v_pk_fma_f32 v[106:107], v[84:85], v[72:73], v[106:107] op_sel:[1,0,0] op_sel_hi:[1,1,1]
	v_pk_fma_f32 v[108:109], v[84:85], v[74:75], v[108:109] op_sel:[1,0,0] op_sel_hi:[1,1,1]
	v_pk_fma_f32 v[110:111], v[84:85], v[76:77], v[110:111] op_sel:[1,0,0] op_sel_hi:[1,1,1]
	s_waitcnt lgkmcnt(7)
	v_lshlrev_b32_e32 v86, 16, v86
	v_lshlrev_b32_e32 v87, 16, v87
	v_lshlrev_b32_e32 v88, 16, v88
	v_lshlrev_b32_e32 v89, 16, v89
	v_lshlrev_b32_e32 v90, 16, v90
	v_lshlrev_b32_e32 v91, 16, v91
	v_lshlrev_b32_e32 v92, 16, v92
	v_lshlrev_b32_e32 v93, 16, v93
	ds_read_u16 v101, v137 offset:11776
	ds_read_u16 v153, v137 offset:12288
	ds_read_u16 v154, v137 offset:12800
	ds_read_u16 v155, v137 offset:13312
	ds_read_u16 v156, v137 offset:13824
	ds_read_u16 v157, v137 offset:14336
	ds_read_u16 v158, v137 offset:14848
	ds_read_u16 v159, v137 offset:15360
	v_pk_fma_f32 v[104:105], v[86:87], v[202:203], v[104:105] op_sel:[0,0,0] op_sel_hi:[0,1,1]
	v_pk_fma_f32 v[106:107], v[86:87], v[204:205], v[106:107] op_sel:[0,0,0] op_sel_hi:[0,1,1]
	v_pk_fma_f32 v[108:109], v[86:87], v[206:207], v[108:109] op_sel:[0,0,0] op_sel_hi:[0,1,1]
	v_pk_fma_f32 v[110:111], v[86:87], v[208:209], v[110:111] op_sel:[0,0,0] op_sel_hi:[0,1,1]
	v_pk_fma_f32 v[112:113], v[86:87], v[210:211], v[134:135] op_sel:[0,0,0] op_sel_hi:[0,1,0]
	v_pk_fma_f32 v[104:105], v[86:87], v[68:69], v[104:105] op_sel:[1,0,0] op_sel_hi:[1,1,1]
	v_pk_fma_f32 v[106:107], v[86:87], v[70:71], v[106:107] op_sel:[1,0,0] op_sel_hi:[1,1,1]
	v_pk_fma_f32 v[108:109], v[86:87], v[72:73], v[108:109] op_sel:[1,0,0] op_sel_hi:[1,1,1]
	v_pk_fma_f32 v[110:111], v[86:87], v[74:75], v[110:111] op_sel:[1,0,0] op_sel_hi:[1,1,1]
	v_pk_fma_f32 v[112:113], v[86:87], v[76:77], v[112:113] op_sel:[1,0,0] op_sel_hi:[1,1,1]
	v_pk_fma_f32 v[104:105], v[88:89], v[200:201], v[104:105] op_sel:[0,0,0] op_sel_hi:[0,1,1]
	v_pk_fma_f32 v[106:107], v[88:89], v[202:203], v[106:107] op_sel:[0,0,0] op_sel_hi:[0,1,1]
	v_pk_fma_f32 v[108:109], v[88:89], v[204:205], v[108:109] op_sel:[0,0,0] op_sel_hi:[0,1,1]
	v_pk_fma_f32 v[110:111], v[88:89], v[206:207], v[110:111] op_sel:[0,0,0] op_sel_hi:[0,1,1]
	v_pk_fma_f32 v[112:113], v[88:89], v[208:209], v[112:113] op_sel:[0,0,0] op_sel_hi:[0,1,1]
	v_pk_fma_f32 v[114:115], v[88:89], v[210:211], v[134:135] op_sel:[0,0,0] op_sel_hi:[0,1,0]
	v_pk_fma_f32 v[104:105], v[88:89], v[66:67], v[104:105] op_sel:[1,0,0] op_sel_hi:[1,1,1]
	v_pk_fma_f32 v[106:107], v[88:89], v[68:69], v[106:107] op_sel:[1,0,0] op_sel_hi:[1,1,1]
	v_pk_fma_f32 v[108:109], v[88:89], v[70:71], v[108:109] op_sel:[1,0,0] op_sel_hi:[1,1,1]
	v_pk_fma_f32 v[110:111], v[88:89], v[72:73], v[110:111] op_sel:[1,0,0] op_sel_hi:[1,1,1]
	v_pk_fma_f32 v[112:113], v[88:89], v[74:75], v[112:113] op_sel:[1,0,0] op_sel_hi:[1,1,1]
	v_pk_fma_f32 v[114:115], v[88:89], v[76:77], v[114:115] op_sel:[1,0,0] op_sel_hi:[1,1,1]
	v_pk_fma_f32 v[104:105], v[90:91], v[198:199], v[104:105] op_sel:[0,0,0] op_sel_hi:[0,1,1]
	v_pk_fma_f32 v[106:107], v[90:91], v[200:201], v[106:107] op_sel:[0,0,0] op_sel_hi:[0,1,1]
	v_pk_fma_f32 v[108:109], v[90:91], v[202:203], v[108:109] op_sel:[0,0,0] op_sel_hi:[0,1,1]
	v_pk_fma_f32 v[110:111], v[90:91], v[204:205], v[110:111] op_sel:[0,0,0] op_sel_hi:[0,1,1]
	v_pk_fma_f32 v[112:113], v[90:91], v[206:207], v[112:113] op_sel:[0,0,0] op_sel_hi:[0,1,1]
	v_pk_fma_f32 v[114:115], v[90:91], v[208:209], v[114:115] op_sel:[0,0,0] op_sel_hi:[0,1,1]
	v_pk_fma_f32 v[116:117], v[90:91], v[210:211], v[134:135] op_sel:[0,0,0] op_sel_hi:[0,1,0]
	v_pk_fma_f32 v[104:105], v[90:91], v[64:65], v[104:105] op_sel:[1,0,0] op_sel_hi:[1,1,1]
	v_pk_fma_f32 v[106:107], v[90:91], v[66:67], v[106:107] op_sel:[1,0,0] op_sel_hi:[1,1,1]
	v_pk_fma_f32 v[108:109], v[90:91], v[68:69], v[108:109] op_sel:[1,0,0] op_sel_hi:[1,1,1]
	v_pk_fma_f32 v[110:111], v[90:91], v[70:71], v[110:111] op_sel:[1,0,0] op_sel_hi:[1,1,1]
	v_pk_fma_f32 v[112:113], v[90:91], v[72:73], v[112:113] op_sel:[1,0,0] op_sel_hi:[1,1,1]
	v_pk_fma_f32 v[114:115], v[90:91], v[74:75], v[114:115] op_sel:[1,0,0] op_sel_hi:[1,1,1]
	v_pk_fma_f32 v[116:117], v[90:91], v[76:77], v[116:117] op_sel:[1,0,0] op_sel_hi:[1,1,1]
	v_pk_fma_f32 v[104:105], v[92:93], v[196:197], v[104:105] op_sel:[0,0,0] op_sel_hi:[0,1,1]
	v_pk_fma_f32 v[106:107], v[92:93], v[198:199], v[106:107] op_sel:[0,0,0] op_sel_hi:[0,1,1]
	v_pk_fma_f32 v[108:109], v[92:93], v[200:201], v[108:109] op_sel:[0,0,0] op_sel_hi:[0,1,1]
	v_pk_fma_f32 v[110:111], v[92:93], v[202:203], v[110:111] op_sel:[0,0,0] op_sel_hi:[0,1,1]
	v_pk_fma_f32 v[112:113], v[92:93], v[204:205], v[112:113] op_sel:[0,0,0] op_sel_hi:[0,1,1]
	v_pk_fma_f32 v[114:115], v[92:93], v[206:207], v[114:115] op_sel:[0,0,0] op_sel_hi:[0,1,1]
	v_pk_fma_f32 v[116:117], v[92:93], v[208:209], v[116:117] op_sel:[0,0,0] op_sel_hi:[0,1,1]
	v_pk_fma_f32 v[118:119], v[92:93], v[210:211], v[134:135] op_sel:[0,0,0] op_sel_hi:[0,1,0]
	v_pk_fma_f32 v[104:105], v[92:93], v[62:63], v[104:105] op_sel:[1,0,0] op_sel_hi:[1,1,1]
	v_pk_fma_f32 v[106:107], v[92:93], v[64:65], v[106:107] op_sel:[1,0,0] op_sel_hi:[1,1,1]
	v_pk_fma_f32 v[108:109], v[92:93], v[66:67], v[108:109] op_sel:[1,0,0] op_sel_hi:[1,1,1]
	v_pk_fma_f32 v[110:111], v[92:93], v[68:69], v[110:111] op_sel:[1,0,0] op_sel_hi:[1,1,1]
	v_pk_fma_f32 v[112:113], v[92:93], v[70:71], v[112:113] op_sel:[1,0,0] op_sel_hi:[1,1,1]
	v_pk_fma_f32 v[114:115], v[92:93], v[72:73], v[114:115] op_sel:[1,0,0] op_sel_hi:[1,1,1]
	v_pk_fma_f32 v[116:117], v[92:93], v[74:75], v[116:117] op_sel:[1,0,0] op_sel_hi:[1,1,1]
	v_pk_fma_f32 v[118:119], v[92:93], v[76:77], v[118:119] op_sel:[1,0,0] op_sel_hi:[1,1,1]
	s_waitcnt lgkmcnt(7)
	v_lshlrev_b32_e32 v94, 16, v94
	v_lshlrev_b32_e32 v95, 16, v95
	v_lshlrev_b32_e32 v96, 16, v96
	v_lshlrev_b32_e32 v97, 16, v97
	v_lshlrev_b32_e32 v98, 16, v98
	v_lshlrev_b32_e32 v99, 16, v99
	v_lshlrev_b32_e32 v100, 16, v100
	v_lshlrev_b32_e32 v101, 16, v101
	ds_read_u16 v160, v137 offset:15872
	ds_read_u16 v161, v137 offset:16384
	ds_read_u16 v162, v137 offset:16896
	ds_read_u16 v163, v137 offset:17408
	ds_read_u16 v164, v137 offset:17920
	ds_read_u16 v165, v137 offset:18432
	ds_read_u16 v166, v137 offset:18944
	ds_read_u16 v167, v137 offset:19456
	v_pk_fma_f32 v[104:105], v[94:95], v[194:195], v[104:105] op_sel:[0,0,0] op_sel_hi:[0,1,1]
	v_pk_fma_f32 v[106:107], v[94:95], v[196:197], v[106:107] op_sel:[0,0,0] op_sel_hi:[0,1,1]
	v_pk_fma_f32 v[108:109], v[94:95], v[198:199], v[108:109] op_sel:[0,0,0] op_sel_hi:[0,1,1]
	v_pk_fma_f32 v[110:111], v[94:95], v[200:201], v[110:111] op_sel:[0,0,0] op_sel_hi:[0,1,1]
	v_pk_fma_f32 v[112:113], v[94:95], v[202:203], v[112:113] op_sel:[0,0,0] op_sel_hi:[0,1,1]
	v_pk_fma_f32 v[114:115], v[94:95], v[204:205], v[114:115] op_sel:[0,0,0] op_sel_hi:[0,1,1]
	v_pk_fma_f32 v[116:117], v[94:95], v[206:207], v[116:117] op_sel:[0,0,0] op_sel_hi:[0,1,1]
	v_pk_fma_f32 v[118:119], v[94:95], v[208:209], v[118:119] op_sel:[0,0,0] op_sel_hi:[0,1,1]
	v_pk_fma_f32 v[104:105], v[94:95], v[60:61], v[104:105] op_sel:[1,0,0] op_sel_hi:[1,1,1]
	v_pk_fma_f32 v[106:107], v[94:95], v[62:63], v[106:107] op_sel:[1,0,0] op_sel_hi:[1,1,1]
	v_pk_fma_f32 v[108:109], v[94:95], v[64:65], v[108:109] op_sel:[1,0,0] op_sel_hi:[1,1,1]
	v_pk_fma_f32 v[110:111], v[94:95], v[66:67], v[110:111] op_sel:[1,0,0] op_sel_hi:[1,1,1]
	v_pk_fma_f32 v[112:113], v[94:95], v[68:69], v[112:113] op_sel:[1,0,0] op_sel_hi:[1,1,1]
	v_pk_fma_f32 v[114:115], v[94:95], v[70:71], v[114:115] op_sel:[1,0,0] op_sel_hi:[1,1,1]
	v_pk_fma_f32 v[116:117], v[94:95], v[72:73], v[116:117] op_sel:[1,0,0] op_sel_hi:[1,1,1]
	v_pk_fma_f32 v[118:119], v[94:95], v[74:75], v[118:119] op_sel:[1,0,0] op_sel_hi:[1,1,1]
	v_pk_fma_f32 v[104:105], v[96:97], v[192:193], v[104:105] op_sel:[0,0,0] op_sel_hi:[0,1,1]
	v_pk_fma_f32 v[106:107], v[96:97], v[194:195], v[106:107] op_sel:[0,0,0] op_sel_hi:[0,1,1]
	v_pk_fma_f32 v[108:109], v[96:97], v[196:197], v[108:109] op_sel:[0,0,0] op_sel_hi:[0,1,1]
	v_pk_fma_f32 v[110:111], v[96:97], v[198:199], v[110:111] op_sel:[0,0,0] op_sel_hi:[0,1,1]
	v_pk_fma_f32 v[112:113], v[96:97], v[200:201], v[112:113] op_sel:[0,0,0] op_sel_hi:[0,1,1]
	v_pk_fma_f32 v[114:115], v[96:97], v[202:203], v[114:115] op_sel:[0,0,0] op_sel_hi:[0,1,1]
	v_pk_fma_f32 v[116:117], v[96:97], v[204:205], v[116:117] op_sel:[0,0,0] op_sel_hi:[0,1,1]
	v_pk_fma_f32 v[118:119], v[96:97], v[206:207], v[118:119] op_sel:[0,0,0] op_sel_hi:[0,1,1]
	v_pk_fma_f32 v[104:105], v[96:97], v[58:59], v[104:105] op_sel:[1,0,0] op_sel_hi:[1,1,1]
	v_pk_fma_f32 v[106:107], v[96:97], v[60:61], v[106:107] op_sel:[1,0,0] op_sel_hi:[1,1,1]
	v_pk_fma_f32 v[108:109], v[96:97], v[62:63], v[108:109] op_sel:[1,0,0] op_sel_hi:[1,1,1]
	v_pk_fma_f32 v[110:111], v[96:97], v[64:65], v[110:111] op_sel:[1,0,0] op_sel_hi:[1,1,1]
	v_pk_fma_f32 v[112:113], v[96:97], v[66:67], v[112:113] op_sel:[1,0,0] op_sel_hi:[1,1,1]
	v_pk_fma_f32 v[114:115], v[96:97], v[68:69], v[114:115] op_sel:[1,0,0] op_sel_hi:[1,1,1]
	v_pk_fma_f32 v[116:117], v[96:97], v[70:71], v[116:117] op_sel:[1,0,0] op_sel_hi:[1,1,1]
	v_pk_fma_f32 v[118:119], v[96:97], v[72:73], v[118:119] op_sel:[1,0,0] op_sel_hi:[1,1,1]
	v_pk_fma_f32 v[104:105], v[98:99], v[190:191], v[104:105] op_sel:[0,0,0] op_sel_hi:[0,1,1]
	v_pk_fma_f32 v[106:107], v[98:99], v[192:193], v[106:107] op_sel:[0,0,0] op_sel_hi:[0,1,1]
	v_pk_fma_f32 v[108:109], v[98:99], v[194:195], v[108:109] op_sel:[0,0,0] op_sel_hi:[0,1,1]
	v_pk_fma_f32 v[110:111], v[98:99], v[196:197], v[110:111] op_sel:[0,0,0] op_sel_hi:[0,1,1]
	v_pk_fma_f32 v[112:113], v[98:99], v[198:199], v[112:113] op_sel:[0,0,0] op_sel_hi:[0,1,1]
	v_pk_fma_f32 v[114:115], v[98:99], v[200:201], v[114:115] op_sel:[0,0,0] op_sel_hi:[0,1,1]
	v_pk_fma_f32 v[116:117], v[98:99], v[202:203], v[116:117] op_sel:[0,0,0] op_sel_hi:[0,1,1]
	v_pk_fma_f32 v[118:119], v[98:99], v[204:205], v[118:119] op_sel:[0,0,0] op_sel_hi:[0,1,1]
	v_pk_fma_f32 v[104:105], v[98:99], v[56:57], v[104:105] op_sel:[1,0,0] op_sel_hi:[1,1,1]
	v_pk_fma_f32 v[106:107], v[98:99], v[58:59], v[106:107] op_sel:[1,0,0] op_sel_hi:[1,1,1]
	v_pk_fma_f32 v[108:109], v[98:99], v[60:61], v[108:109] op_sel:[1,0,0] op_sel_hi:[1,1,1]
	v_pk_fma_f32 v[110:111], v[98:99], v[62:63], v[110:111] op_sel:[1,0,0] op_sel_hi:[1,1,1]
	v_pk_fma_f32 v[112:113], v[98:99], v[64:65], v[112:113] op_sel:[1,0,0] op_sel_hi:[1,1,1]
	v_pk_fma_f32 v[114:115], v[98:99], v[66:67], v[114:115] op_sel:[1,0,0] op_sel_hi:[1,1,1]
	v_pk_fma_f32 v[116:117], v[98:99], v[68:69], v[116:117] op_sel:[1,0,0] op_sel_hi:[1,1,1]
	v_pk_fma_f32 v[118:119], v[98:99], v[70:71], v[118:119] op_sel:[1,0,0] op_sel_hi:[1,1,1]
	v_pk_fma_f32 v[104:105], v[100:101], v[188:189], v[104:105] op_sel:[0,0,0] op_sel_hi:[0,1,1]
	v_pk_fma_f32 v[106:107], v[100:101], v[190:191], v[106:107] op_sel:[0,0,0] op_sel_hi:[0,1,1]
	v_pk_fma_f32 v[108:109], v[100:101], v[192:193], v[108:109] op_sel:[0,0,0] op_sel_hi:[0,1,1]
	v_pk_fma_f32 v[110:111], v[100:101], v[194:195], v[110:111] op_sel:[0,0,0] op_sel_hi:[0,1,1]
	v_pk_fma_f32 v[112:113], v[100:101], v[196:197], v[112:113] op_sel:[0,0,0] op_sel_hi:[0,1,1]
	v_pk_fma_f32 v[114:115], v[100:101], v[198:199], v[114:115] op_sel:[0,0,0] op_sel_hi:[0,1,1]
	v_pk_fma_f32 v[116:117], v[100:101], v[200:201], v[116:117] op_sel:[0,0,0] op_sel_hi:[0,1,1]
	v_pk_fma_f32 v[118:119], v[100:101], v[202:203], v[118:119] op_sel:[0,0,0] op_sel_hi:[0,1,1]
	v_pk_fma_f32 v[104:105], v[100:101], v[54:55], v[104:105] op_sel:[1,0,0] op_sel_hi:[1,1,1]
	v_pk_fma_f32 v[106:107], v[100:101], v[56:57], v[106:107] op_sel:[1,0,0] op_sel_hi:[1,1,1]
	v_pk_fma_f32 v[108:109], v[100:101], v[58:59], v[108:109] op_sel:[1,0,0] op_sel_hi:[1,1,1]
	v_pk_fma_f32 v[110:111], v[100:101], v[60:61], v[110:111] op_sel:[1,0,0] op_sel_hi:[1,1,1]
	v_pk_fma_f32 v[112:113], v[100:101], v[62:63], v[112:113] op_sel:[1,0,0] op_sel_hi:[1,1,1]
	v_pk_fma_f32 v[114:115], v[100:101], v[64:65], v[114:115] op_sel:[1,0,0] op_sel_hi:[1,1,1]
	v_pk_fma_f32 v[116:117], v[100:101], v[66:67], v[116:117] op_sel:[1,0,0] op_sel_hi:[1,1,1]
	v_pk_fma_f32 v[118:119], v[100:101], v[68:69], v[118:119] op_sel:[1,0,0] op_sel_hi:[1,1,1]
	s_waitcnt lgkmcnt(7)
	v_lshlrev_b32_e32 v153, 16, v153
	v_lshlrev_b32_e32 v154, 16, v154
	v_lshlrev_b32_e32 v155, 16, v155
	v_lshlrev_b32_e32 v156, 16, v156
	v_lshlrev_b32_e32 v157, 16, v157
	v_lshlrev_b32_e32 v158, 16, v158
	v_lshlrev_b32_e32 v159, 16, v159
	v_lshlrev_b32_e32 v160, 16, v160
	ds_read_u16 v168, v137 offset:19968
	ds_read_u16 v169, v137 offset:20480
	ds_read_u16 v170, v137 offset:20992
	ds_read_u16 v120, v137 offset:21504
	ds_read_u16 v121, v137 offset:22016
	ds_read_u16 v122, v137 offset:22528
	ds_read_u16 v123, v137 offset:23040
	v_pk_fma_f32 v[104:105], v[152:153], v[186:187], v[104:105] op_sel:[1,0,0] op_sel_hi:[1,1,1]
	v_pk_fma_f32 v[106:107], v[152:153], v[188:189], v[106:107] op_sel:[1,0,0] op_sel_hi:[1,1,1]
	v_pk_fma_f32 v[108:109], v[152:153], v[190:191], v[108:109] op_sel:[1,0,0] op_sel_hi:[1,1,1]
	v_pk_fma_f32 v[110:111], v[152:153], v[192:193], v[110:111] op_sel:[1,0,0] op_sel_hi:[1,1,1]
	v_pk_fma_f32 v[112:113], v[152:153], v[194:195], v[112:113] op_sel:[1,0,0] op_sel_hi:[1,1,1]
	v_pk_fma_f32 v[114:115], v[152:153], v[196:197], v[114:115] op_sel:[1,0,0] op_sel_hi:[1,1,1]
	v_pk_fma_f32 v[116:117], v[152:153], v[198:199], v[116:117] op_sel:[1,0,0] op_sel_hi:[1,1,1]
	v_pk_fma_f32 v[118:119], v[152:153], v[200:201], v[118:119] op_sel:[1,0,0] op_sel_hi:[1,1,1]
	v_pk_fma_f32 v[104:105], v[154:155], v[52:53], v[104:105] op_sel:[0,0,0] op_sel_hi:[0,1,1]
	v_pk_fma_f32 v[106:107], v[154:155], v[54:55], v[106:107] op_sel:[0,0,0] op_sel_hi:[0,1,1]
	v_pk_fma_f32 v[108:109], v[154:155], v[56:57], v[108:109] op_sel:[0,0,0] op_sel_hi:[0,1,1]
	v_pk_fma_f32 v[110:111], v[154:155], v[58:59], v[110:111] op_sel:[0,0,0] op_sel_hi:[0,1,1]
	v_pk_fma_f32 v[112:113], v[154:155], v[60:61], v[112:113] op_sel:[0,0,0] op_sel_hi:[0,1,1]
	v_pk_fma_f32 v[114:115], v[154:155], v[62:63], v[114:115] op_sel:[0,0,0] op_sel_hi:[0,1,1]
	v_pk_fma_f32 v[116:117], v[154:155], v[64:65], v[116:117] op_sel:[0,0,0] op_sel_hi:[0,1,1]
	v_pk_fma_f32 v[118:119], v[154:155], v[66:67], v[118:119] op_sel:[0,0,0] op_sel_hi:[0,1,1]
	v_pk_fma_f32 v[104:105], v[154:155], v[184:185], v[104:105] op_sel:[1,0,0] op_sel_hi:[1,1,1]
	v_pk_fma_f32 v[106:107], v[154:155], v[186:187], v[106:107] op_sel:[1,0,0] op_sel_hi:[1,1,1]
	v_pk_fma_f32 v[108:109], v[154:155], v[188:189], v[108:109] op_sel:[1,0,0] op_sel_hi:[1,1,1]
	v_pk_fma_f32 v[110:111], v[154:155], v[190:191], v[110:111] op_sel:[1,0,0] op_sel_hi:[1,1,1]
	v_pk_fma_f32 v[112:113], v[154:155], v[192:193], v[112:113] op_sel:[1,0,0] op_sel_hi:[1,1,1]
	v_pk_fma_f32 v[114:115], v[154:155], v[194:195], v[114:115] op_sel:[1,0,0] op_sel_hi:[1,1,1]
	v_pk_fma_f32 v[116:117], v[154:155], v[196:197], v[116:117] op_sel:[1,0,0] op_sel_hi:[1,1,1]
	v_pk_fma_f32 v[118:119], v[154:155], v[198:199], v[118:119] op_sel:[1,0,0] op_sel_hi:[1,1,1]
	v_pk_fma_f32 v[104:105], v[156:157], v[50:51], v[104:105] op_sel:[0,0,0] op_sel_hi:[0,1,1]
	v_pk_fma_f32 v[106:107], v[156:157], v[52:53], v[106:107] op_sel:[0,0,0] op_sel_hi:[0,1,1]
	v_pk_fma_f32 v[108:109], v[156:157], v[54:55], v[108:109] op_sel:[0,0,0] op_sel_hi:[0,1,1]
	v_pk_fma_f32 v[110:111], v[156:157], v[56:57], v[110:111] op_sel:[0,0,0] op_sel_hi:[0,1,1]
	v_pk_fma_f32 v[112:113], v[156:157], v[58:59], v[112:113] op_sel:[0,0,0] op_sel_hi:[0,1,1]
	v_pk_fma_f32 v[114:115], v[156:157], v[60:61], v[114:115] op_sel:[0,0,0] op_sel_hi:[0,1,1]
	v_pk_fma_f32 v[116:117], v[156:157], v[62:63], v[116:117] op_sel:[0,0,0] op_sel_hi:[0,1,1]
	v_pk_fma_f32 v[118:119], v[156:157], v[64:65], v[118:119] op_sel:[0,0,0] op_sel_hi:[0,1,1]
	v_pk_fma_f32 v[104:105], v[156:157], v[182:183], v[104:105] op_sel:[1,0,0] op_sel_hi:[1,1,1]
	v_pk_fma_f32 v[106:107], v[156:157], v[184:185], v[106:107] op_sel:[1,0,0] op_sel_hi:[1,1,1]
	v_pk_fma_f32 v[108:109], v[156:157], v[186:187], v[108:109] op_sel:[1,0,0] op_sel_hi:[1,1,1]
	v_pk_fma_f32 v[110:111], v[156:157], v[188:189], v[110:111] op_sel:[1,0,0] op_sel_hi:[1,1,1]
	v_pk_fma_f32 v[112:113], v[156:157], v[190:191], v[112:113] op_sel:[1,0,0] op_sel_hi:[1,1,1]
	v_pk_fma_f32 v[114:115], v[156:157], v[192:193], v[114:115] op_sel:[1,0,0] op_sel_hi:[1,1,1]
	v_pk_fma_f32 v[116:117], v[156:157], v[194:195], v[116:117] op_sel:[1,0,0] op_sel_hi:[1,1,1]
	v_pk_fma_f32 v[118:119], v[156:157], v[196:197], v[118:119] op_sel:[1,0,0] op_sel_hi:[1,1,1]
	v_pk_fma_f32 v[104:105], v[158:159], v[48:49], v[104:105] op_sel:[0,0,0] op_sel_hi:[0,1,1]
	v_pk_fma_f32 v[106:107], v[158:159], v[50:51], v[106:107] op_sel:[0,0,0] op_sel_hi:[0,1,1]
	v_pk_fma_f32 v[108:109], v[158:159], v[52:53], v[108:109] op_sel:[0,0,0] op_sel_hi:[0,1,1]
	v_pk_fma_f32 v[110:111], v[158:159], v[54:55], v[110:111] op_sel:[0,0,0] op_sel_hi:[0,1,1]
	v_pk_fma_f32 v[112:113], v[158:159], v[56:57], v[112:113] op_sel:[0,0,0] op_sel_hi:[0,1,1]
	v_pk_fma_f32 v[114:115], v[158:159], v[58:59], v[114:115] op_sel:[0,0,0] op_sel_hi:[0,1,1]
	v_pk_fma_f32 v[116:117], v[158:159], v[60:61], v[116:117] op_sel:[0,0,0] op_sel_hi:[0,1,1]
	v_pk_fma_f32 v[118:119], v[158:159], v[62:63], v[118:119] op_sel:[0,0,0] op_sel_hi:[0,1,1]
	v_pk_fma_f32 v[104:105], v[158:159], v[180:181], v[104:105] op_sel:[1,0,0] op_sel_hi:[1,1,1]
	v_pk_fma_f32 v[106:107], v[158:159], v[182:183], v[106:107] op_sel:[1,0,0] op_sel_hi:[1,1,1]
	v_pk_fma_f32 v[108:109], v[158:159], v[184:185], v[108:109] op_sel:[1,0,0] op_sel_hi:[1,1,1]
	v_pk_fma_f32 v[110:111], v[158:159], v[186:187], v[110:111] op_sel:[1,0,0] op_sel_hi:[1,1,1]
	v_pk_fma_f32 v[112:113], v[158:159], v[188:189], v[112:113] op_sel:[1,0,0] op_sel_hi:[1,1,1]
	v_pk_fma_f32 v[114:115], v[158:159], v[190:191], v[114:115] op_sel:[1,0,0] op_sel_hi:[1,1,1]
	v_pk_fma_f32 v[116:117], v[158:159], v[192:193], v[116:117] op_sel:[1,0,0] op_sel_hi:[1,1,1]
	v_pk_fma_f32 v[118:119], v[158:159], v[194:195], v[118:119] op_sel:[1,0,0] op_sel_hi:[1,1,1]
	v_pk_fma_f32 v[104:105], v[160:161], v[46:47], v[104:105] op_sel:[0,0,0] op_sel_hi:[0,1,1]
	v_pk_fma_f32 v[106:107], v[160:161], v[48:49], v[106:107] op_sel:[0,0,0] op_sel_hi:[0,1,1]
	v_pk_fma_f32 v[108:109], v[160:161], v[50:51], v[108:109] op_sel:[0,0,0] op_sel_hi:[0,1,1]
	v_pk_fma_f32 v[110:111], v[160:161], v[52:53], v[110:111] op_sel:[0,0,0] op_sel_hi:[0,1,1]
	v_pk_fma_f32 v[112:113], v[160:161], v[54:55], v[112:113] op_sel:[0,0,0] op_sel_hi:[0,1,1]
	v_pk_fma_f32 v[114:115], v[160:161], v[56:57], v[114:115] op_sel:[0,0,0] op_sel_hi:[0,1,1]
	v_pk_fma_f32 v[116:117], v[160:161], v[58:59], v[116:117] op_sel:[0,0,0] op_sel_hi:[0,1,1]
	v_pk_fma_f32 v[118:119], v[160:161], v[60:61], v[118:119] op_sel:[0,0,0] op_sel_hi:[0,1,1]
	s_waitcnt lgkmcnt(6)
	v_lshlrev_b32_e32 v161, 16, v161
	v_lshlrev_b32_e32 v162, 16, v162
	v_lshlrev_b32_e32 v163, 16, v163
	v_lshlrev_b32_e32 v164, 16, v164
	v_lshlrev_b32_e32 v165, 16, v165
	v_lshlrev_b32_e32 v166, 16, v166
	v_lshlrev_b32_e32 v167, 16, v167
	v_lshlrev_b32_e32 v168, 16, v168
	v_pk_fma_f32 v[106:107], v[160:161], v[180:181], v[106:107] op_sel:[1,0,0] op_sel_hi:[1,1,1]
	v_pk_fma_f32 v[108:109], v[160:161], v[182:183], v[108:109] op_sel:[1,0,0] op_sel_hi:[1,1,1]
	v_pk_fma_f32 v[110:111], v[160:161], v[184:185], v[110:111] op_sel:[1,0,0] op_sel_hi:[1,1,1]
	v_pk_fma_f32 v[112:113], v[160:161], v[186:187], v[112:113] op_sel:[1,0,0] op_sel_hi:[1,1,1]
	v_pk_fma_f32 v[114:115], v[160:161], v[188:189], v[114:115] op_sel:[1,0,0] op_sel_hi:[1,1,1]
	v_pk_fma_f32 v[116:117], v[160:161], v[190:191], v[116:117] op_sel:[1,0,0] op_sel_hi:[1,1,1]
	v_pk_fma_f32 v[118:119], v[160:161], v[192:193], v[118:119] op_sel:[1,0,0] op_sel_hi:[1,1,1]
	v_pk_fma_f32 v[106:107], v[162:163], v[46:47], v[106:107] op_sel:[0,0,0] op_sel_hi:[0,1,1]
	v_pk_fma_f32 v[108:109], v[162:163], v[48:49], v[108:109] op_sel:[0,0,0] op_sel_hi:[0,1,1]
	v_pk_fma_f32 v[110:111], v[162:163], v[50:51], v[110:111] op_sel:[0,0,0] op_sel_hi:[0,1,1]
	v_pk_fma_f32 v[112:113], v[162:163], v[52:53], v[112:113] op_sel:[0,0,0] op_sel_hi:[0,1,1]
	v_pk_fma_f32 v[114:115], v[162:163], v[54:55], v[114:115] op_sel:[0,0,0] op_sel_hi:[0,1,1]
	v_pk_fma_f32 v[116:117], v[162:163], v[56:57], v[116:117] op_sel:[0,0,0] op_sel_hi:[0,1,1]
	v_pk_fma_f32 v[118:119], v[162:163], v[58:59], v[118:119] op_sel:[0,0,0] op_sel_hi:[0,1,1]
	v_pk_fma_f32 v[108:109], v[162:163], v[180:181], v[108:109] op_sel:[1,0,0] op_sel_hi:[1,1,1]
	v_pk_fma_f32 v[110:111], v[162:163], v[182:183], v[110:111] op_sel:[1,0,0] op_sel_hi:[1,1,1]
	v_pk_fma_f32 v[112:113], v[162:163], v[184:185], v[112:113] op_sel:[1,0,0] op_sel_hi:[1,1,1]
	v_pk_fma_f32 v[114:115], v[162:163], v[186:187], v[114:115] op_sel:[1,0,0] op_sel_hi:[1,1,1]
	v_pk_fma_f32 v[116:117], v[162:163], v[188:189], v[116:117] op_sel:[1,0,0] op_sel_hi:[1,1,1]
	v_pk_fma_f32 v[118:119], v[162:163], v[190:191], v[118:119] op_sel:[1,0,0] op_sel_hi:[1,1,1]
	v_pk_fma_f32 v[108:109], v[164:165], v[46:47], v[108:109] op_sel:[0,0,0] op_sel_hi:[0,1,1]
	v_pk_fma_f32 v[110:111], v[164:165], v[48:49], v[110:111] op_sel:[0,0,0] op_sel_hi:[0,1,1]
	v_pk_fma_f32 v[112:113], v[164:165], v[50:51], v[112:113] op_sel:[0,0,0] op_sel_hi:[0,1,1]
	v_pk_fma_f32 v[114:115], v[164:165], v[52:53], v[114:115] op_sel:[0,0,0] op_sel_hi:[0,1,1]
	v_pk_fma_f32 v[116:117], v[164:165], v[54:55], v[116:117] op_sel:[0,0,0] op_sel_hi:[0,1,1]
	v_pk_fma_f32 v[118:119], v[164:165], v[56:57], v[118:119] op_sel:[0,0,0] op_sel_hi:[0,1,1]
	v_pk_fma_f32 v[110:111], v[164:165], v[180:181], v[110:111] op_sel:[1,0,0] op_sel_hi:[1,1,1]
	v_pk_fma_f32 v[112:113], v[164:165], v[182:183], v[112:113] op_sel:[1,0,0] op_sel_hi:[1,1,1]
	v_pk_fma_f32 v[114:115], v[164:165], v[184:185], v[114:115] op_sel:[1,0,0] op_sel_hi:[1,1,1]
	v_pk_fma_f32 v[116:117], v[164:165], v[186:187], v[116:117] op_sel:[1,0,0] op_sel_hi:[1,1,1]
	v_pk_fma_f32 v[118:119], v[164:165], v[188:189], v[118:119] op_sel:[1,0,0] op_sel_hi:[1,1,1]
	v_pk_fma_f32 v[110:111], v[166:167], v[46:47], v[110:111] op_sel:[0,0,0] op_sel_hi:[0,1,1]
	v_pk_fma_f32 v[112:113], v[166:167], v[48:49], v[112:113] op_sel:[0,0,0] op_sel_hi:[0,1,1]
	v_pk_fma_f32 v[114:115], v[166:167], v[50:51], v[114:115] op_sel:[0,0,0] op_sel_hi:[0,1,1]
	v_pk_fma_f32 v[116:117], v[166:167], v[52:53], v[116:117] op_sel:[0,0,0] op_sel_hi:[0,1,1]
	v_pk_fma_f32 v[118:119], v[166:167], v[54:55], v[118:119] op_sel:[0,0,0] op_sel_hi:[0,1,1]
	v_pk_fma_f32 v[112:113], v[166:167], v[180:181], v[112:113] op_sel:[1,0,0] op_sel_hi:[1,1,1]
	v_pk_fma_f32 v[114:115], v[166:167], v[182:183], v[114:115] op_sel:[1,0,0] op_sel_hi:[1,1,1]
	v_pk_fma_f32 v[116:117], v[166:167], v[184:185], v[116:117] op_sel:[1,0,0] op_sel_hi:[1,1,1]
	v_pk_fma_f32 v[118:119], v[166:167], v[186:187], v[118:119] op_sel:[1,0,0] op_sel_hi:[1,1,1]
	v_pk_fma_f32 v[112:113], v[168:169], v[46:47], v[112:113] op_sel:[0,0,0] op_sel_hi:[0,1,1]
	v_pk_fma_f32 v[114:115], v[168:169], v[48:49], v[114:115] op_sel:[0,0,0] op_sel_hi:[0,1,1]
	v_pk_fma_f32 v[116:117], v[168:169], v[50:51], v[116:117] op_sel:[0,0,0] op_sel_hi:[0,1,1]
	v_pk_fma_f32 v[118:119], v[168:169], v[52:53], v[118:119] op_sel:[0,0,0] op_sel_hi:[0,1,1]
	s_waitcnt lgkmcnt(0)
	v_lshlrev_b32_e32 v169, 16, v169
	v_lshlrev_b32_e32 v170, 16, v170
	v_lshlrev_b32_e32 v120, 16, v120
	v_lshlrev_b32_e32 v121, 16, v121
	v_lshlrev_b32_e32 v122, 16, v122
	v_lshlrev_b32_e32 v123, 16, v123
	v_pk_fma_f32 v[114:115], v[168:169], v[180:181], v[114:115] op_sel:[1,0,0] op_sel_hi:[1,1,1]
	v_pk_fma_f32 v[116:117], v[168:169], v[182:183], v[116:117] op_sel:[1,0,0] op_sel_hi:[1,1,1]
	v_pk_fma_f32 v[118:119], v[168:169], v[184:185], v[118:119] op_sel:[1,0,0] op_sel_hi:[1,1,1]
	v_pk_fma_f32 v[114:115], v[170:171], v[46:47], v[114:115] op_sel:[0,0,0] op_sel_hi:[0,1,1]
	v_pk_fma_f32 v[116:117], v[170:171], v[48:49], v[116:117] op_sel:[0,0,0] op_sel_hi:[0,1,1]
	v_pk_fma_f32 v[118:119], v[170:171], v[50:51], v[118:119] op_sel:[0,0,0] op_sel_hi:[0,1,1]
	v_pk_fma_f32 v[116:117], v[120:121], v[180:181], v[116:117] op_sel:[0,0,0] op_sel_hi:[0,1,1]
	v_pk_fma_f32 v[118:119], v[120:121], v[182:183], v[118:119] op_sel:[0,0,0] op_sel_hi:[0,1,1]
	v_pk_fma_f32 v[116:117], v[120:121], v[46:47], v[116:117] op_sel:[1,0,0] op_sel_hi:[1,1,1]
	v_pk_fma_f32 v[118:119], v[120:121], v[48:49], v[118:119] op_sel:[1,0,0] op_sel_hi:[1,1,1]
	v_pk_fma_f32 v[118:119], v[122:123], v[180:181], v[118:119] op_sel:[0,0,0] op_sel_hi:[0,1,1]
	v_pk_fma_f32 v[118:119], v[122:123], v[46:47], v[118:119] op_sel:[1,0,0] op_sel_hi:[1,1,1]
	ds_write2st64_b32 v145, v104, v105 offset0:220 offset1:224
	ds_write2st64_b32 v145, v106, v107 offset0:228 offset1:232
	ds_write2st64_b32 v145, v108, v109 offset0:236 offset1:240
	ds_write2st64_b32 v145, v110, v111 offset0:244 offset1:248
	ds_write_b32 v145, v112 offset:64512
	ds_write_b32 v146, v113
	ds_write_b32 v147, v114
	ds_write_b32 v148, v115
	ds_write_b32 v149, v116
	ds_write_b32 v150, v117
	ds_write_b32 v151, v118
	ds_write_b32 v152, v119
	ds_read_u16 v212, v137 offset:31744
	ds_read_u16 v213, v137 offset:32256
	ds_read_u16 v214, v137 offset:32768
	ds_read_u16 v215, v137 offset:33280
	ds_read_u16 v216, v137 offset:33792
	ds_read_u16 v217, v137 offset:34304
	ds_read_u16 v218, v137 offset:34816
	ds_read_u16 v219, v137 offset:35328
	ds_read_u16 v78, v137 offset:35840
	ds_read_u16 v79, v137 offset:36352
	ds_read_u16 v80, v137 offset:36864
	ds_read_u16 v81, v137 offset:37376
	s_waitcnt lgkmcnt(4)
	ds_read_u16 v82, v137 offset:37888
	ds_read_u16 v83, v137 offset:38400
	ds_read_u16 v84, v137 offset:38912
	ds_read_u16 v85, v137 offset:39424
	ds_read_u16 v86, v137 offset:39936
	ds_read_u16 v87, v137 offset:40448
	ds_read_u16 v88, v137 offset:40960
	ds_read_u16 v89, v137 offset:41472
	ds_read_u16 v90, v137 offset:41984
	ds_read_u16 v91, v137 offset:42496
	ds_read_u16 v92, v137 offset:43008
	v_lshlrev_b32_e32 v212, 16, v212
	v_add_f32_e32 v122, 0, v212
	v_lshlrev_b32_e32 v213, 16, v213
	v_add_f32_e32 v120, v122, v213
	v_lshlrev_b32_e32 v214, 16, v214
	v_add_f32_e32 v121, v120, v214
	v_lshlrev_b32_e32 v215, 16, v215
	v_add_f32_e32 v123, v121, v215
	v_lshlrev_b32_e32 v216, 16, v216
	v_add_f32_e32 v125, v123, v216
	v_lshlrev_b32_e32 v217, 16, v217
	v_add_f32_e32 v164, v125, v217
	v_lshlrev_b32_e32 v218, 16, v218
	v_add_f32_e32 v163, v164, v218
	v_lshlrev_b32_e32 v219, 16, v219
	v_add_f32_e32 v162, v163, v219
	s_waitcnt lgkmcnt(7)
	ds_read_u16 v93, v137 offset:43520
	v_lshlrev_b32_e32 v78, 16, v78
	v_add_f32_e32 v161, v162, v78
	v_lshlrev_b32_e32 v79, 16, v79
	v_add_f32_e32 v160, v161, v79
	v_lshlrev_b32_e32 v80, 16, v80
	v_add_f32_e32 v159, v160, v80
	v_lshlrev_b32_e32 v81, 16, v81
	v_add_f32_e32 v158, v159, v81
	v_lshlrev_b32_e32 v82, 16, v82
	v_add_f32_e32 v157, v158, v82
	v_lshlrev_b32_e32 v83, 16, v83
	v_add_f32_e32 v156, v157, v83
	v_lshlrev_b32_e32 v84, 16, v84
	v_add_f32_e32 v155, v156, v84
	v_lshlrev_b32_e32 v85, 16, v85
	v_add_f32_e32 v154, v155, v85
	s_waitcnt lgkmcnt(0)
	v_lshlrev_b32_e32 v86, 16, v86
	v_add_f32_e32 v153, v154, v86
	v_lshlrev_b32_e32 v87, 16, v87
	v_add_f32_e32 v1, v153, v87
	v_lshlrev_b32_e32 v88, 16, v88
	v_add_f32_e32 v169, v1, v88
	v_lshlrev_b32_e32 v89, 16, v89
	v_add_f32_e32 v168, v169, v89
	v_lshlrev_b32_e32 v90, 16, v90
	v_add_f32_e32 v166, v168, v90
	v_lshlrev_b32_e32 v91, 16, v91
	v_add_f32_e32 v167, v166, v91
	v_lshlrev_b32_e32 v92, 16, v92
	v_add_f32_e32 v165, v167, v92
	v_lshlrev_b32_e32 v93, 16, v93
	v_add_f32_e32 v170, v165, v93
	v_add_u32_e32 v2, s59, v139
	s_and_saveexec_b64 s[12:13], s[14:15]
	s_xor_b64 s[12:13], exec, s[12:13]
	s_cbranch_execz .LBB0_603
	ds_read_u16 v127, v137 offset:45568
	ds_read_u16 v124, v137 offset:46080
	ds_read_u16 v3, v137 offset:44032
	ds_read_u16 v126, v137 offset:46592
	ds_read_u16 v36, v137 offset:44544
	ds_read_u16 v128, v137 offset:47104
	ds_read_u16 v37, v137 offset:45056
	s_waitcnt lgkmcnt(4)
	v_lshlrev_b32_e32 v3, 16, v3
	v_add_f32_e32 v171, v170, v3
	s_waitcnt lgkmcnt(2)
	v_lshlrev_b32_e32 v3, 16, v36
	v_add_f32_e32 v175, v171, v3
	s_waitcnt lgkmcnt(0)
	v_lshlrev_b32_e32 v3, 16, v37
	v_sub_f32_e32 v172, v161, v162
	v_add_f32_e32 v174, v175, v3
	v_cmp_lt_i32_e32 vcc, 1, v138
	s_mov_b64 s[42:43], 0
	s_mov_b64 s[26:27], 0
	s_and_saveexec_b64 s[20:21], vcc
	s_xor_b64 s[50:51], exec, s[20:21]
	s_cbranch_execz .LBB0_596
	v_cmp_eq_u32_e32 vcc, 2, v138
	s_mov_b64 s[20:21], -1
	s_and_saveexec_b64 s[52:53], vcc
	s_cbranch_execz .LBB0_595
	v_add_u32_e32 v3, -4, v2
	v_or_b32_e32 v112, 4, v2
	v_max_i32_e32 v3, s30, v3
	v_min_i32_e32 v36, s31, v112
	v_sub_u32_e32 v3, v36, v3
	v_cvt_f32_i32_e32 v3, v3
	v_sub_f32_e32 v37, v158, v123
	v_or_b32_e32 v110, 1, v2
	v_sub_f32_e32 v39, v157, v125
	v_rcp_iflag_f32_e32 v3, v3
	v_ashrrev_i32_e32 v111, 31, v110
	v_or_b32_e32 v114, 2, v2
	v_sub_f32_e32 v104, v156, v164
	v_fma_f32 v3, v3, v37, -v172
	v_cvt_pk_bf16_f32 v38, v3, s0
	v_ashrrev_i32_e32 v3, 31, v2
	v_lshlrev_b64 v[36:37], 11, v[2:3]
	v_lshl_add_u64 v[36:37], v[44:45], 0, v[36:37]
	global_store_short v[36:37], v38, off
	v_add_u32_e32 v3, -3, v2
	v_or_b32_e32 v36, 5, v2
	v_max_i32_e32 v3, s30, v3
	v_min_i32_e32 v37, s31, v36
	v_sub_u32_e32 v3, v37, v3
	v_cvt_f32_i32_e32 v3, v3
	v_sub_f32_e32 v38, v160, v161
	v_ashrrev_i32_e32 v115, 31, v114
	v_or_b32_e32 v116, 3, v2
	v_rcp_iflag_f32_e32 v3, v3
	v_ashrrev_i32_e32 v117, 31, v116
	v_lshlrev_b64 v[106:107], 11, v[116:117]
	v_lshl_add_u64 v[106:107], v[44:45], 0, v[106:107]
	v_fma_f32 v3, v3, v39, -v38
	v_lshlrev_b64 v[38:39], 11, v[110:111]
	v_cvt_pk_bf16_f32 v3, v3, s0
	v_lshl_add_u64 v[38:39], v[44:45], 0, v[38:39]
	global_store_short v[38:39], v3, off
	v_add_u32_e32 v3, -2, v2
	v_or_b32_e32 v38, 6, v2
	v_max_i32_e32 v3, s30, v3
	v_min_i32_e32 v37, s31, v38
	v_sub_u32_e32 v3, v37, v3
	v_cvt_f32_i32_e32 v3, v3
	v_sub_f32_e32 v39, v159, v160
	v_ashrrev_i32_e32 v113, 31, v112
	v_lshlrev_b64 v[108:109], 11, v[112:113]
	v_rcp_iflag_f32_e32 v3, v3
	v_lshl_add_u64 v[108:109], v[44:45], 0, v[108:109]
	v_or_b32_e32 v118, 13, v2
	v_ashrrev_i32_e32 v119, 31, v118
	v_fma_f32 v3, v3, v104, -v39
	v_lshlrev_b64 v[104:105], 11, v[114:115]
	v_cvt_pk_bf16_f32 v3, v3, s0
	v_lshl_add_u64 v[104:105], v[44:45], 0, v[104:105]
	global_store_short v[104:105], v3, off
	v_add_u32_e32 v3, -1, v2
	v_or_b32_e32 v104, 7, v2
	v_max_i32_e32 v3, s30, v3
	v_min_i32_e32 v37, s31, v104
	v_sub_u32_e32 v3, v37, v3
	v_cvt_f32_i32_e32 v3, v3
	v_sub_f32_e32 v39, v158, v159
	v_sub_f32_e32 v105, v155, v163
	s_xor_b64 s[20:21], exec, -1
	v_rcp_iflag_f32_e32 v3, v3
	s_nop 0
	v_fma_f32 v3, v3, v105, -v39
	v_cvt_pk_bf16_f32 v3, v3, s0
	global_store_short v[106:107], v3, off
	v_or_b32_e32 v106, 8, v2
	v_max_i32_e32 v3, s30, v2
	v_min_i32_e32 v37, s31, v106
	v_sub_u32_e32 v3, v37, v3
	v_cvt_f32_i32_e32 v3, v3
	v_sub_f32_e32 v39, v157, v158
	v_sub_f32_e32 v105, v154, v162
	v_ashrrev_i32_e32 v107, 31, v106
	v_rcp_iflag_f32_e32 v3, v3
	s_nop 0
	v_fma_f32 v3, v3, v105, -v39
	v_cvt_pk_bf16_f32 v3, v3, s0
	global_store_short v[108:109], v3, off
	v_or_b32_e32 v108, 9, v2
	v_max_i32_e32 v3, s30, v110
	v_min_i32_e32 v37, s31, v108
	v_sub_u32_e32 v3, v37, v3
	v_cvt_f32_i32_e32 v3, v3
	v_sub_f32_e32 v39, v156, v157
	v_sub_f32_e32 v105, v153, v161
	v_ashrrev_i32_e32 v37, 31, v36
	v_rcp_iflag_f32_e32 v3, v3
	v_lshlrev_b64 v[110:111], 11, v[36:37]
	v_lshl_add_u64 v[110:111], v[44:45], 0, v[110:111]
	v_ashrrev_i32_e32 v109, 31, v108
	v_fma_f32 v3, v3, v105, -v39
	v_cvt_pk_bf16_f32 v3, v3, s0
	global_store_short v[110:111], v3, off
	v_or_b32_e32 v110, 10, v2
	v_max_i32_e32 v3, s30, v114
	v_min_i32_e32 v37, s31, v110
	v_sub_u32_e32 v3, v37, v3
	v_cvt_f32_i32_e32 v3, v3
	v_sub_f32_e32 v39, v155, v156
	v_sub_f32_e32 v105, v1, v160
	v_ashrrev_i32_e32 v111, 31, v110
	v_rcp_iflag_f32_e32 v3, v3
	s_nop 0
	v_fma_f32 v3, v3, v105, -v39
	v_ashrrev_i32_e32 v39, 31, v38
	v_lshlrev_b64 v[114:115], 11, v[38:39]
	v_cvt_pk_bf16_f32 v3, v3, s0
	v_lshl_add_u64 v[114:115], v[44:45], 0, v[114:115]
	global_store_short v[114:115], v3, off
	v_or_b32_e32 v114, 11, v2
	v_max_i32_e32 v3, s30, v116
	v_min_i32_e32 v37, s31, v114
	v_sub_u32_e32 v3, v37, v3
	v_cvt_f32_i32_e32 v3, v3
	v_sub_f32_e32 v39, v154, v155
	v_sub_f32_e32 v105, v169, v159
	v_ashrrev_i32_e32 v115, 31, v114
	v_rcp_iflag_f32_e32 v3, v3
	s_nop 0
	v_fma_f32 v3, v3, v105, -v39
	v_ashrrev_i32_e32 v105, 31, v104
	v_lshlrev_b64 v[116:117], 11, v[104:105]
	v_cvt_pk_bf16_f32 v3, v3, s0
	v_lshl_add_u64 v[116:117], v[44:45], 0, v[116:117]
	global_store_short v[116:117], v3, off
	v_or_b32_e32 v116, 12, v2
	v_max_i32_e32 v3, s30, v112
	v_min_i32_e32 v37, s31, v116
	v_sub_u32_e32 v3, v37, v3
	v_cvt_f32_i32_e32 v3, v3
	v_sub_f32_e32 v39, v153, v154
	v_sub_f32_e32 v105, v168, v158
	v_lshlrev_b64 v[112:113], 11, v[106:107]
	v_rcp_iflag_f32_e32 v3, v3
	v_lshl_add_u64 v[112:113], v[44:45], 0, v[112:113]
	v_sub_f32_e32 v37, v1, v153
	v_ashrrev_i32_e32 v117, 31, v116
	v_fma_f32 v3, v3, v105, -v39
	v_cvt_pk_bf16_f32 v3, v3, s0
	global_store_short v[112:113], v3, off
	v_max_i32_e32 v3, s30, v36
	v_min_i32_e32 v36, s31, v118
	v_sub_u32_e32 v3, v36, v3
	v_cvt_f32_i32_e32 v3, v3
	v_sub_f32_e32 v39, v166, v157
	v_or_b32_e32 v112, 14, v2
	v_ashrrev_i32_e32 v113, 31, v112
	v_rcp_iflag_f32_e32 v3, v3
	s_nop 0
	v_fma_f32 v3, v3, v39, -v37
	v_lshlrev_b64 v[36:37], 11, v[108:109]
	v_cvt_pk_bf16_f32 v3, v3, s0
	v_lshl_add_u64 v[36:37], v[44:45], 0, v[36:37]
	global_store_short v[36:37], v3, off
	v_max_i32_e32 v3, s30, v38
	v_min_i32_e32 v36, s31, v112
	v_sub_u32_e32 v3, v36, v3
	v_cvt_f32_i32_e32 v3, v3
	v_sub_f32_e32 v37, v169, v1
	v_sub_f32_e32 v38, v167, v156
	v_sub_f32_e32 v39, v165, v155
	v_rcp_iflag_f32_e32 v3, v3
	s_nop 0
	v_fma_f32 v3, v3, v38, -v37
	v_lshlrev_b64 v[36:37], 11, v[110:111]
	v_cvt_pk_bf16_f32 v3, v3, s0
	v_lshl_add_u64 v[36:37], v[44:45], 0, v[36:37]
	global_store_short v[36:37], v3, off
	v_or_b32_e32 v36, 15, v2
	v_max_i32_e32 v3, s30, v104
	v_min_i32_e32 v37, s31, v36
	v_sub_u32_e32 v3, v37, v3
	v_cvt_f32_i32_e32 v3, v3
	v_sub_f32_e32 v38, v168, v169
	v_max_i32_e32 v37, s30, v106
	v_rcp_iflag_f32_e32 v3, v3
	s_nop 0
	v_fma_f32 v3, v3, v39, -v38
	v_lshlrev_b64 v[38:39], 11, v[114:115]
	v_cvt_pk_bf16_f32 v3, v3, s0
	v_lshl_add_u64 v[38:39], v[44:45], 0, v[38:39]
	global_store_short v[38:39], v3, off
	v_add_u32_e32 v3, 16, v2
	v_min_i32_e32 v3, s31, v3
	v_sub_u32_e32 v3, v3, v37
	v_cvt_f32_i32_e32 v3, v3
	v_sub_f32_e32 v38, v166, v168
	v_sub_f32_e32 v39, v170, v154
	v_max_i32_e32 v37, s30, v108
	v_rcp_iflag_f32_e32 v3, v3
	s_nop 0
	v_fma_f32 v3, v3, v39, -v38
	v_lshlrev_b64 v[38:39], 11, v[116:117]
	v_cvt_pk_bf16_f32 v3, v3, s0
	v_lshl_add_u64 v[38:39], v[44:45], 0, v[38:39]
	global_store_short v[38:39], v3, off
	v_add_u32_e32 v3, 17, v2
	v_min_i32_e32 v3, s31, v3
	v_sub_u32_e32 v3, v3, v37
	v_cvt_f32_i32_e32 v3, v3
	v_sub_f32_e32 v38, v167, v166
	v_sub_f32_e32 v39, v171, v153
	v_max_i32_e32 v37, s30, v110
	v_rcp_iflag_f32_e32 v3, v3
	s_nop 0
	v_fma_f32 v3, v3, v39, -v38
	v_lshlrev_b64 v[38:39], 11, v[118:119]
	v_cvt_pk_bf16_f32 v3, v3, s0
	v_lshl_add_u64 v[38:39], v[44:45], 0, v[38:39]
	global_store_short v[38:39], v3, off
	v_add_u32_e32 v3, 18, v2
	v_min_i32_e32 v3, s31, v3
	v_sub_u32_e32 v3, v3, v37
	v_cvt_f32_i32_e32 v3, v3
	v_sub_f32_e32 v38, v165, v167
	v_sub_f32_e32 v39, v175, v1
	v_max_i32_e32 v37, s30, v114
	v_rcp_iflag_f32_e32 v3, v3
	s_nop 0
	v_fma_f32 v3, v3, v39, -v38
	v_lshlrev_b64 v[38:39], 11, v[112:113]
	v_cvt_pk_bf16_f32 v3, v3, s0
	v_lshl_add_u64 v[38:39], v[44:45], 0, v[38:39]
	global_store_short v[38:39], v3, off
	v_add_u32_e32 v3, 19, v2
	v_min_i32_e32 v38, s31, v3
	v_sub_f32_e32 v3, v174, v169
	v_sub_u32_e32 v38, v38, v37
